# grid barrier: XCD leaders keep two polls of the arrival counter in flight (software-pipelined poll loop)
# baseline (speedup 1.0000x reference)
.LBB0_668:
	s_or_b64 exec, exec, s[8:9]
	s_waitcnt vmcnt(0)
	v_readfirstlane_b32 s6, v2
	v_cvt_f32_u32_e32 v2, v0
	v_sub_u32_e32 v3, 0, v0
	v_add_u32_e32 v1, s6, v1
	v_readlane_b32 s6, v245, 13
	v_rcp_iflag_f32_e32 v2, v2
	v_readlane_b32 s7, v245, 14
	s_mov_b64 s[8:9], -1
	v_mul_f32_e32 v2, 0x4f7ffffe, v2
	v_cvt_u32_f32_e32 v2, v2
	v_mul_lo_u32 v3, v3, v2
	v_mul_hi_u32 v3, v2, v3
	v_add_u32_e32 v2, v2, v3
	v_mul_hi_u32 v2, v1, v2
	v_mul_lo_u32 v3, v2, v0
	v_sub_u32_e32 v3, v1, v3
	v_cmp_ge_u32_e32 vcc, v3, v0
	v_add_u32_e32 v4, 1, v2
	v_add_u32_e32 v1, 1, v1
	v_cndmask_b32_e32 v2, v2, v4, vcc
	v_sub_u32_e32 v4, v3, v0
	v_cndmask_b32_e32 v3, v3, v4, vcc
	v_cmp_ge_u32_e32 vcc, v3, v0
	v_add_u32_e32 v3, 1, v2
	s_nop 0
	v_cndmask_b32_e32 v2, v2, v3, vcc
	v_mul_lo_u32 v3, v0, v2
	v_add_u32_e32 v0, v3, v0
	v_cmp_ne_u32_e32 vcc, v1, v0
	v_mov_b32_e32 v4, v0
	v_mov_b64_e32 v[0:1], s[6:7]
	s_and_saveexec_b64 s[6:7], vcc
	s_cbranch_execz .LBB0_680
	v_readlane_b32 s8, v245, 11
	v_readlane_b32 s9, v245, 12
	s_mov_b64 s[10:11], 0
	s_mov_b32 s20, 0
	s_nop 4
	global_load_dword v0, v137, s[8:9] sc1
.Ltp_loop:
	global_load_dword v5, v137, s[8:9] sc1
	s_waitcnt vmcnt(1)
	v_cmp_ge_u32_e32 vcc, v0, v4
	s_cbranch_vccnz .Ltp_done
	global_load_dword v0, v137, s[8:9] sc1
	s_waitcnt vmcnt(1)
	v_cmp_ge_u32_e32 vcc, v5, v4
	s_cbranch_vccnz .Ltp_done
	s_add_i32 s20, s20, 1
	s_cmp_lt_u32 s20, 0x400000
	s_cbranch_scc1 .Ltp_loop
	s_mov_b64 s[10:11], exec
.Ltp_done:
	s_waitcnt vmcnt(0)
	s_mov_b64 s[8:9], 0
